# modulation-table GEMV inner loop rewritten: packed even/odd-k f32 partial sums per row straight from the LDS reads, no shuffle moves
# speedup vs baseline: 1.0014x; 1.0014x over previous
.LBB0_409:
	v_mov_b64_e32 v[190:191], 0
	v_mov_b64_e32 v[192:193], 0
	v_mov_b64_e32 v[194:195], 0
	v_mov_b64_e32 v[196:197], 0
	v_mov_b64_e32 v[198:199], 0
	v_mov_b64_e32 v[200:201], 0
	v_mov_b64_e32 v[202:203], 0
	v_mov_b64_e32 v[204:205], 0
	v_mov_b64_e32 v[206:207], 0
	v_mov_b64_e32 v[208:209], 0
	v_mov_b64_e32 v[210:211], 0
	v_mov_b64_e32 v[212:213], 0
	v_mov_b64_e32 v[214:215], 0
	v_mov_b64_e32 v[216:217], 0
	v_mov_b64_e32 v[218:219], 0
	v_mov_b64_e32 v[220:221], 0
	v_mov_b64_e32 v[222:223], 0
	v_mov_b64_e32 v[148:149], v[10:11]
	v_add_co_u32_e64 v150, s[0:1], s11, v148
	s_nop 1
	v_addc_co_u32_e64 v151, s[0:1], -1, v149, s[0:1]
	v_add_co_u32_e64 v152, s[0:1], s12, v148
	s_nop 1
	v_addc_co_u32_e64 v153, s[0:1], -1, v149, s[0:1]
	v_add_co_u32_e64 v154, s[0:1], s13, v148
	global_load_dword v100, v[150:151], off
	global_load_dword v101, v[152:153], off
	v_addc_co_u32_e64 v155, s[0:1], -1, v149, s[0:1]
	global_load_dword v103, v[148:149], off
	global_load_dword v102, v[154:155], off
	v_lshl_add_u64 v[148:149], v[148:149], 0, s[2:3]
	v_add_co_u32_e64 v150, s[0:1], s11, v148
	s_nop 1
	v_addc_co_u32_e64 v151, s[0:1], -1, v149, s[0:1]
	v_add_co_u32_e64 v152, s[0:1], s12, v148
	s_nop 1
	v_addc_co_u32_e64 v153, s[0:1], -1, v149, s[0:1]
	v_add_co_u32_e64 v154, s[0:1], s13, v148
	global_load_dword v104, v[150:151], off
	global_load_dword v105, v[152:153], off
	v_addc_co_u32_e64 v155, s[0:1], -1, v149, s[0:1]
	global_load_dword v107, v[148:149], off
	global_load_dword v106, v[154:155], off
	v_lshl_add_u64 v[148:149], v[148:149], 0, s[2:3]
	v_add_co_u32_e64 v150, s[0:1], s11, v148
	s_nop 1
	v_addc_co_u32_e64 v151, s[0:1], -1, v149, s[0:1]
	v_add_co_u32_e64 v152, s[0:1], s12, v148
	s_nop 1
	v_addc_co_u32_e64 v153, s[0:1], -1, v149, s[0:1]
	v_add_co_u32_e64 v154, s[0:1], s13, v148
	global_load_dword v108, v[150:151], off
	global_load_dword v109, v[152:153], off
	v_addc_co_u32_e64 v155, s[0:1], -1, v149, s[0:1]
	global_load_dword v111, v[148:149], off
	global_load_dword v110, v[154:155], off
	v_lshl_add_u64 v[148:149], v[148:149], 0, s[2:3]
.Lmodq_loop:
	v_add_u32_e32 v31, s6, v3
	s_add_i32 s6, s6, 16
	v_add_co_u32_e64 v150, s[0:1], s11, v148
	s_nop 1
	v_addc_co_u32_e64 v151, s[0:1], -1, v149, s[0:1]
	v_add_co_u32_e64 v152, s[0:1], s12, v148
	s_nop 1
	v_addc_co_u32_e64 v153, s[0:1], -1, v149, s[0:1]
	v_add_co_u32_e64 v154, s[0:1], s13, v148
	global_load_dword v112, v[150:151], off
	global_load_dword v113, v[152:153], off
	v_addc_co_u32_e64 v155, s[0:1], -1, v149, s[0:1]
	global_load_dword v115, v[148:149], off
	global_load_dword v114, v[154:155], off
	v_lshl_add_u64 v[148:149], v[148:149], 0, s[2:3]
	ds_read_b128 v[32:35], v31
	ds_read_b128 v[36:39], v31 offset:4096
	ds_read_b128 v[40:43], v31 offset:8192
	ds_read_b128 v[44:47], v31 offset:12288
	ds_read_b128 v[48:51], v31 offset:16384
	ds_read_b128 v[52:55], v31 offset:20480
	ds_read_b128 v[56:59], v31 offset:24576
	ds_read_b128 v[60:63], v31 offset:28672
	ds_read_b128 v[64:67], v31 offset:32768
	ds_read_b128 v[68:71], v31 offset:36864
	ds_read_b128 v[72:75], v31 offset:40960
	ds_read_b128 v[76:79], v31 offset:45056
	ds_read_b128 v[80:83], v31 offset:49152
	ds_read_b128 v[84:87], v31 offset:53248
	ds_read_b128 v[88:91], v31 offset:57344
	ds_read_b128 v[92:95], v31 offset:61440
	v_add_u32_e32 v31, 0x10000, v31
	ds_read_b128 v[96:99], v31
	s_waitcnt vmcnt(12)
	s_waitcnt lgkmcnt(15)
	v_pk_fma_f32 v[190:191], v[32:33], v[100:101], v[190:191]
	v_pk_fma_f32 v[190:191], v[34:35], v[102:103], v[190:191]
	s_waitcnt lgkmcnt(15)
	v_pk_fma_f32 v[192:193], v[36:37], v[100:101], v[192:193]
	v_pk_fma_f32 v[192:193], v[38:39], v[102:103], v[192:193]
	s_waitcnt lgkmcnt(14)
	v_pk_fma_f32 v[194:195], v[40:41], v[100:101], v[194:195]
	v_pk_fma_f32 v[194:195], v[42:43], v[102:103], v[194:195]
	s_waitcnt lgkmcnt(13)
	v_pk_fma_f32 v[196:197], v[44:45], v[100:101], v[196:197]
	v_pk_fma_f32 v[196:197], v[46:47], v[102:103], v[196:197]
	s_waitcnt lgkmcnt(12)
	v_pk_fma_f32 v[198:199], v[48:49], v[100:101], v[198:199]
	v_pk_fma_f32 v[198:199], v[50:51], v[102:103], v[198:199]
	s_waitcnt lgkmcnt(11)
	v_pk_fma_f32 v[200:201], v[52:53], v[100:101], v[200:201]
	v_pk_fma_f32 v[200:201], v[54:55], v[102:103], v[200:201]
	s_waitcnt lgkmcnt(10)
	v_pk_fma_f32 v[202:203], v[56:57], v[100:101], v[202:203]
	v_pk_fma_f32 v[202:203], v[58:59], v[102:103], v[202:203]
	s_waitcnt lgkmcnt(9)
	v_pk_fma_f32 v[204:205], v[60:61], v[100:101], v[204:205]
	v_pk_fma_f32 v[204:205], v[62:63], v[102:103], v[204:205]
	s_waitcnt lgkmcnt(8)
	v_pk_fma_f32 v[206:207], v[64:65], v[100:101], v[206:207]
	v_pk_fma_f32 v[206:207], v[66:67], v[102:103], v[206:207]
	s_waitcnt lgkmcnt(7)
	v_pk_fma_f32 v[208:209], v[68:69], v[100:101], v[208:209]
	v_pk_fma_f32 v[208:209], v[70:71], v[102:103], v[208:209]
	s_waitcnt lgkmcnt(6)
	v_pk_fma_f32 v[210:211], v[72:73], v[100:101], v[210:211]
	v_pk_fma_f32 v[210:211], v[74:75], v[102:103], v[210:211]
	s_waitcnt lgkmcnt(5)
	v_pk_fma_f32 v[212:213], v[76:77], v[100:101], v[212:213]
	v_pk_fma_f32 v[212:213], v[78:79], v[102:103], v[212:213]
	s_waitcnt lgkmcnt(4)
	v_pk_fma_f32 v[214:215], v[80:81], v[100:101], v[214:215]
	v_pk_fma_f32 v[214:215], v[82:83], v[102:103], v[214:215]
	s_waitcnt lgkmcnt(3)
	v_pk_fma_f32 v[216:217], v[84:85], v[100:101], v[216:217]
	v_pk_fma_f32 v[216:217], v[86:87], v[102:103], v[216:217]
	s_waitcnt lgkmcnt(2)
	v_pk_fma_f32 v[218:219], v[88:89], v[100:101], v[218:219]
	v_pk_fma_f32 v[218:219], v[90:91], v[102:103], v[218:219]
	s_waitcnt lgkmcnt(1)
	v_pk_fma_f32 v[220:221], v[92:93], v[100:101], v[220:221]
	v_pk_fma_f32 v[220:221], v[94:95], v[102:103], v[220:221]
	s_waitcnt lgkmcnt(0)
	v_pk_fma_f32 v[222:223], v[96:97], v[100:101], v[222:223]
	v_pk_fma_f32 v[222:223], v[98:99], v[102:103], v[222:223]
	v_add_u32_e32 v31, s6, v3
	s_add_i32 s6, s6, 16
	v_add_co_u32_e64 v150, s[0:1], s11, v148
	s_nop 1
	v_addc_co_u32_e64 v151, s[0:1], -1, v149, s[0:1]
	v_add_co_u32_e64 v152, s[0:1], s12, v148
	s_nop 1
	v_addc_co_u32_e64 v153, s[0:1], -1, v149, s[0:1]
	v_add_co_u32_e64 v154, s[0:1], s13, v148
	global_load_dword v100, v[150:151], off
	global_load_dword v101, v[152:153], off
	v_addc_co_u32_e64 v155, s[0:1], -1, v149, s[0:1]
	global_load_dword v103, v[148:149], off
	global_load_dword v102, v[154:155], off
	v_lshl_add_u64 v[148:149], v[148:149], 0, s[2:3]
	ds_read_b128 v[32:35], v31
	ds_read_b128 v[36:39], v31 offset:4096
	ds_read_b128 v[40:43], v31 offset:8192
	ds_read_b128 v[44:47], v31 offset:12288
	ds_read_b128 v[48:51], v31 offset:16384
	ds_read_b128 v[52:55], v31 offset:20480
	ds_read_b128 v[56:59], v31 offset:24576
	ds_read_b128 v[60:63], v31 offset:28672
	ds_read_b128 v[64:67], v31 offset:32768
	ds_read_b128 v[68:71], v31 offset:36864
	ds_read_b128 v[72:75], v31 offset:40960
	ds_read_b128 v[76:79], v31 offset:45056
	ds_read_b128 v[80:83], v31 offset:49152
	ds_read_b128 v[84:87], v31 offset:53248
	ds_read_b128 v[88:91], v31 offset:57344
	ds_read_b128 v[92:95], v31 offset:61440
	v_add_u32_e32 v31, 0x10000, v31
	ds_read_b128 v[96:99], v31
	s_waitcnt vmcnt(12)
	s_waitcnt lgkmcnt(15)
	v_pk_fma_f32 v[190:191], v[32:33], v[104:105], v[190:191]
	v_pk_fma_f32 v[190:191], v[34:35], v[106:107], v[190:191]
	s_waitcnt lgkmcnt(15)
	v_pk_fma_f32 v[192:193], v[36:37], v[104:105], v[192:193]
	v_pk_fma_f32 v[192:193], v[38:39], v[106:107], v[192:193]
	s_waitcnt lgkmcnt(14)
	v_pk_fma_f32 v[194:195], v[40:41], v[104:105], v[194:195]
	v_pk_fma_f32 v[194:195], v[42:43], v[106:107], v[194:195]
	s_waitcnt lgkmcnt(13)
	v_pk_fma_f32 v[196:197], v[44:45], v[104:105], v[196:197]
	v_pk_fma_f32 v[196:197], v[46:47], v[106:107], v[196:197]
	s_waitcnt lgkmcnt(12)
	v_pk_fma_f32 v[198:199], v[48:49], v[104:105], v[198:199]
	v_pk_fma_f32 v[198:199], v[50:51], v[106:107], v[198:199]
	s_waitcnt lgkmcnt(11)
	v_pk_fma_f32 v[200:201], v[52:53], v[104:105], v[200:201]
	v_pk_fma_f32 v[200:201], v[54:55], v[106:107], v[200:201]
	s_waitcnt lgkmcnt(10)
	v_pk_fma_f32 v[202:203], v[56:57], v[104:105], v[202:203]
	v_pk_fma_f32 v[202:203], v[58:59], v[106:107], v[202:203]
	s_waitcnt lgkmcnt(9)
	v_pk_fma_f32 v[204:205], v[60:61], v[104:105], v[204:205]
	v_pk_fma_f32 v[204:205], v[62:63], v[106:107], v[204:205]
	s_waitcnt lgkmcnt(8)
	v_pk_fma_f32 v[206:207], v[64:65], v[104:105], v[206:207]
	v_pk_fma_f32 v[206:207], v[66:67], v[106:107], v[206:207]
	s_waitcnt lgkmcnt(7)
	v_pk_fma_f32 v[208:209], v[68:69], v[104:105], v[208:209]
	v_pk_fma_f32 v[208:209], v[70:71], v[106:107], v[208:209]
	s_waitcnt lgkmcnt(6)
	v_pk_fma_f32 v[210:211], v[72:73], v[104:105], v[210:211]
	v_pk_fma_f32 v[210:211], v[74:75], v[106:107], v[210:211]
	s_waitcnt lgkmcnt(5)
	v_pk_fma_f32 v[212:213], v[76:77], v[104:105], v[212:213]
	v_pk_fma_f32 v[212:213], v[78:79], v[106:107], v[212:213]
	s_waitcnt lgkmcnt(4)
	v_pk_fma_f32 v[214:215], v[80:81], v[104:105], v[214:215]
	v_pk_fma_f32 v[214:215], v[82:83], v[106:107], v[214:215]
	s_waitcnt lgkmcnt(3)
	v_pk_fma_f32 v[216:217], v[84:85], v[104:105], v[216:217]
	v_pk_fma_f32 v[216:217], v[86:87], v[106:107], v[216:217]
	s_waitcnt lgkmcnt(2)
	v_pk_fma_f32 v[218:219], v[88:89], v[104:105], v[218:219]
	v_pk_fma_f32 v[218:219], v[90:91], v[106:107], v[218:219]
	s_waitcnt lgkmcnt(1)
	v_pk_fma_f32 v[220:221], v[92:93], v[104:105], v[220:221]
	v_pk_fma_f32 v[220:221], v[94:95], v[106:107], v[220:221]
	s_waitcnt lgkmcnt(0)
	v_pk_fma_f32 v[222:223], v[96:97], v[104:105], v[222:223]
	v_pk_fma_f32 v[222:223], v[98:99], v[106:107], v[222:223]
	v_add_u32_e32 v31, s6, v3
	s_add_i32 s6, s6, 16
	v_add_co_u32_e64 v150, s[0:1], s11, v148
	s_nop 1
	v_addc_co_u32_e64 v151, s[0:1], -1, v149, s[0:1]
	v_add_co_u32_e64 v152, s[0:1], s12, v148
	s_nop 1
	v_addc_co_u32_e64 v153, s[0:1], -1, v149, s[0:1]
	v_add_co_u32_e64 v154, s[0:1], s13, v148
	global_load_dword v104, v[150:151], off
	global_load_dword v105, v[152:153], off
	v_addc_co_u32_e64 v155, s[0:1], -1, v149, s[0:1]
	global_load_dword v107, v[148:149], off
	global_load_dword v106, v[154:155], off
	v_lshl_add_u64 v[148:149], v[148:149], 0, s[2:3]
	ds_read_b128 v[32:35], v31
	ds_read_b128 v[36:39], v31 offset:4096
	ds_read_b128 v[40:43], v31 offset:8192
	ds_read_b128 v[44:47], v31 offset:12288
	ds_read_b128 v[48:51], v31 offset:16384
	ds_read_b128 v[52:55], v31 offset:20480
	ds_read_b128 v[56:59], v31 offset:24576
	ds_read_b128 v[60:63], v31 offset:28672
	ds_read_b128 v[64:67], v31 offset:32768
	ds_read_b128 v[68:71], v31 offset:36864
	ds_read_b128 v[72:75], v31 offset:40960
	ds_read_b128 v[76:79], v31 offset:45056
	ds_read_b128 v[80:83], v31 offset:49152
	ds_read_b128 v[84:87], v31 offset:53248
	ds_read_b128 v[88:91], v31 offset:57344
	ds_read_b128 v[92:95], v31 offset:61440
	v_add_u32_e32 v31, 0x10000, v31
	ds_read_b128 v[96:99], v31
	s_waitcnt vmcnt(12)
	s_waitcnt lgkmcnt(15)
	v_pk_fma_f32 v[190:191], v[32:33], v[108:109], v[190:191]
	v_pk_fma_f32 v[190:191], v[34:35], v[110:111], v[190:191]
	s_waitcnt lgkmcnt(15)
	v_pk_fma_f32 v[192:193], v[36:37], v[108:109], v[192:193]
	v_pk_fma_f32 v[192:193], v[38:39], v[110:111], v[192:193]
	s_waitcnt lgkmcnt(14)
	v_pk_fma_f32 v[194:195], v[40:41], v[108:109], v[194:195]
	v_pk_fma_f32 v[194:195], v[42:43], v[110:111], v[194:195]
	s_waitcnt lgkmcnt(13)
	v_pk_fma_f32 v[196:197], v[44:45], v[108:109], v[196:197]
	v_pk_fma_f32 v[196:197], v[46:47], v[110:111], v[196:197]
	s_waitcnt lgkmcnt(12)
	v_pk_fma_f32 v[198:199], v[48:49], v[108:109], v[198:199]
	v_pk_fma_f32 v[198:199], v[50:51], v[110:111], v[198:199]
	s_waitcnt lgkmcnt(11)
	v_pk_fma_f32 v[200:201], v[52:53], v[108:109], v[200:201]
	v_pk_fma_f32 v[200:201], v[54:55], v[110:111], v[200:201]
	s_waitcnt lgkmcnt(10)
	v_pk_fma_f32 v[202:203], v[56:57], v[108:109], v[202:203]
	v_pk_fma_f32 v[202:203], v[58:59], v[110:111], v[202:203]
	s_waitcnt lgkmcnt(9)
	v_pk_fma_f32 v[204:205], v[60:61], v[108:109], v[204:205]
	v_pk_fma_f32 v[204:205], v[62:63], v[110:111], v[204:205]
	s_waitcnt lgkmcnt(8)
	v_pk_fma_f32 v[206:207], v[64:65], v[108:109], v[206:207]
	v_pk_fma_f32 v[206:207], v[66:67], v[110:111], v[206:207]
	s_waitcnt lgkmcnt(7)
	v_pk_fma_f32 v[208:209], v[68:69], v[108:109], v[208:209]
	v_pk_fma_f32 v[208:209], v[70:71], v[110:111], v[208:209]
	s_waitcnt lgkmcnt(6)
	v_pk_fma_f32 v[210:211], v[72:73], v[108:109], v[210:211]
	v_pk_fma_f32 v[210:211], v[74:75], v[110:111], v[210:211]
	s_waitcnt lgkmcnt(5)
	v_pk_fma_f32 v[212:213], v[76:77], v[108:109], v[212:213]
	v_pk_fma_f32 v[212:213], v[78:79], v[110:111], v[212:213]
	s_waitcnt lgkmcnt(4)
	v_pk_fma_f32 v[214:215], v[80:81], v[108:109], v[214:215]
	v_pk_fma_f32 v[214:215], v[82:83], v[110:111], v[214:215]
	s_waitcnt lgkmcnt(3)
	v_pk_fma_f32 v[216:217], v[84:85], v[108:109], v[216:217]
	v_pk_fma_f32 v[216:217], v[86:87], v[110:111], v[216:217]
	s_waitcnt lgkmcnt(2)
	v_pk_fma_f32 v[218:219], v[88:89], v[108:109], v[218:219]
	v_pk_fma_f32 v[218:219], v[90:91], v[110:111], v[218:219]
	s_waitcnt lgkmcnt(1)
	v_pk_fma_f32 v[220:221], v[92:93], v[108:109], v[220:221]
	v_pk_fma_f32 v[220:221], v[94:95], v[110:111], v[220:221]
	s_waitcnt lgkmcnt(0)
	v_pk_fma_f32 v[222:223], v[96:97], v[108:109], v[222:223]
	v_pk_fma_f32 v[222:223], v[98:99], v[110:111], v[222:223]
	v_add_u32_e32 v31, s6, v3
	s_add_i32 s6, s6, 16
	v_add_co_u32_e64 v150, s[0:1], s11, v148
	s_nop 1
	v_addc_co_u32_e64 v151, s[0:1], -1, v149, s[0:1]
	v_add_co_u32_e64 v152, s[0:1], s12, v148
	s_nop 1
	v_addc_co_u32_e64 v153, s[0:1], -1, v149, s[0:1]
	v_add_co_u32_e64 v154, s[0:1], s13, v148
	global_load_dword v108, v[150:151], off
	global_load_dword v109, v[152:153], off
	v_addc_co_u32_e64 v155, s[0:1], -1, v149, s[0:1]
	global_load_dword v111, v[148:149], off
	global_load_dword v110, v[154:155], off
	v_lshl_add_u64 v[148:149], v[148:149], 0, s[2:3]
	ds_read_b128 v[32:35], v31
	ds_read_b128 v[36:39], v31 offset:4096
	ds_read_b128 v[40:43], v31 offset:8192
	ds_read_b128 v[44:47], v31 offset:12288
	ds_read_b128 v[48:51], v31 offset:16384
	ds_read_b128 v[52:55], v31 offset:20480
	ds_read_b128 v[56:59], v31 offset:24576
	ds_read_b128 v[60:63], v31 offset:28672
	ds_read_b128 v[64:67], v31 offset:32768
	ds_read_b128 v[68:71], v31 offset:36864
	ds_read_b128 v[72:75], v31 offset:40960
	ds_read_b128 v[76:79], v31 offset:45056
	ds_read_b128 v[80:83], v31 offset:49152
	ds_read_b128 v[84:87], v31 offset:53248
	ds_read_b128 v[88:91], v31 offset:57344
	ds_read_b128 v[92:95], v31 offset:61440
	v_add_u32_e32 v31, 0x10000, v31
	ds_read_b128 v[96:99], v31
	s_waitcnt vmcnt(12)
	s_waitcnt lgkmcnt(15)
	v_pk_fma_f32 v[190:191], v[32:33], v[112:113], v[190:191]
	v_pk_fma_f32 v[190:191], v[34:35], v[114:115], v[190:191]
	s_waitcnt lgkmcnt(15)
	v_pk_fma_f32 v[192:193], v[36:37], v[112:113], v[192:193]
	v_pk_fma_f32 v[192:193], v[38:39], v[114:115], v[192:193]
	s_waitcnt lgkmcnt(14)
	v_pk_fma_f32 v[194:195], v[40:41], v[112:113], v[194:195]
	v_pk_fma_f32 v[194:195], v[42:43], v[114:115], v[194:195]
	s_waitcnt lgkmcnt(13)
	v_pk_fma_f32 v[196:197], v[44:45], v[112:113], v[196:197]
	v_pk_fma_f32 v[196:197], v[46:47], v[114:115], v[196:197]
	s_waitcnt lgkmcnt(12)
	v_pk_fma_f32 v[198:199], v[48:49], v[112:113], v[198:199]
	v_pk_fma_f32 v[198:199], v[50:51], v[114:115], v[198:199]
	s_waitcnt lgkmcnt(11)
	v_pk_fma_f32 v[200:201], v[52:53], v[112:113], v[200:201]
	v_pk_fma_f32 v[200:201], v[54:55], v[114:115], v[200:201]
	s_waitcnt lgkmcnt(10)
	v_pk_fma_f32 v[202:203], v[56:57], v[112:113], v[202:203]
	v_pk_fma_f32 v[202:203], v[58:59], v[114:115], v[202:203]
	s_waitcnt lgkmcnt(9)
	v_pk_fma_f32 v[204:205], v[60:61], v[112:113], v[204:205]
	v_pk_fma_f32 v[204:205], v[62:63], v[114:115], v[204:205]
	s_waitcnt lgkmcnt(8)
	v_pk_fma_f32 v[206:207], v[64:65], v[112:113], v[206:207]
	v_pk_fma_f32 v[206:207], v[66:67], v[114:115], v[206:207]
	s_waitcnt lgkmcnt(7)
	v_pk_fma_f32 v[208:209], v[68:69], v[112:113], v[208:209]
	v_pk_fma_f32 v[208:209], v[70:71], v[114:115], v[208:209]
	s_waitcnt lgkmcnt(6)
	v_pk_fma_f32 v[210:211], v[72:73], v[112:113], v[210:211]
	v_pk_fma_f32 v[210:211], v[74:75], v[114:115], v[210:211]
	s_waitcnt lgkmcnt(5)
	v_pk_fma_f32 v[212:213], v[76:77], v[112:113], v[212:213]
	v_pk_fma_f32 v[212:213], v[78:79], v[114:115], v[212:213]
	s_waitcnt lgkmcnt(4)
	v_pk_fma_f32 v[214:215], v[80:81], v[112:113], v[214:215]
	v_pk_fma_f32 v[214:215], v[82:83], v[114:115], v[214:215]
	s_waitcnt lgkmcnt(3)
	v_pk_fma_f32 v[216:217], v[84:85], v[112:113], v[216:217]
	v_pk_fma_f32 v[216:217], v[86:87], v[114:115], v[216:217]
	s_waitcnt lgkmcnt(2)
	v_pk_fma_f32 v[218:219], v[88:89], v[112:113], v[218:219]
	v_pk_fma_f32 v[218:219], v[90:91], v[114:115], v[218:219]
	s_waitcnt lgkmcnt(1)
	v_pk_fma_f32 v[220:221], v[92:93], v[112:113], v[220:221]
	v_pk_fma_f32 v[220:221], v[94:95], v[114:115], v[220:221]
	s_waitcnt lgkmcnt(0)
	v_pk_fma_f32 v[222:223], v[96:97], v[112:113], v[222:223]
	v_pk_fma_f32 v[222:223], v[98:99], v[114:115], v[222:223]
	s_cmpk_eq_i32 s6, 0x1c0
	s_cbranch_scc0 .Lmodq_loop
	v_add_u32_e32 v31, s6, v3
	s_add_i32 s6, s6, 16
	v_add_co_u32_e64 v150, s[0:1], s11, v148
	s_nop 1
	v_addc_co_u32_e64 v151, s[0:1], -1, v149, s[0:1]
	v_add_co_u32_e64 v152, s[0:1], s12, v148
	s_nop 1
	v_addc_co_u32_e64 v153, s[0:1], -1, v149, s[0:1]
	v_add_co_u32_e64 v154, s[0:1], s13, v148
	global_load_dword v112, v[150:151], off
	global_load_dword v113, v[152:153], off
	v_addc_co_u32_e64 v155, s[0:1], -1, v149, s[0:1]
	global_load_dword v115, v[148:149], off
	global_load_dword v114, v[154:155], off
	v_lshl_add_u64 v[148:149], v[148:149], 0, s[2:3]
	ds_read_b128 v[32:35], v31
	ds_read_b128 v[36:39], v31 offset:4096
	ds_read_b128 v[40:43], v31 offset:8192
	ds_read_b128 v[44:47], v31 offset:12288
	ds_read_b128 v[48:51], v31 offset:16384
	ds_read_b128 v[52:55], v31 offset:20480
	ds_read_b128 v[56:59], v31 offset:24576
	ds_read_b128 v[60:63], v31 offset:28672
	ds_read_b128 v[64:67], v31 offset:32768
	ds_read_b128 v[68:71], v31 offset:36864
	ds_read_b128 v[72:75], v31 offset:40960
	ds_read_b128 v[76:79], v31 offset:45056
	ds_read_b128 v[80:83], v31 offset:49152
	ds_read_b128 v[84:87], v31 offset:53248
	ds_read_b128 v[88:91], v31 offset:57344
	ds_read_b128 v[92:95], v31 offset:61440
	v_add_u32_e32 v31, 0x10000, v31
	ds_read_b128 v[96:99], v31
	s_waitcnt vmcnt(12)
	s_waitcnt lgkmcnt(15)
	v_pk_fma_f32 v[190:191], v[32:33], v[100:101], v[190:191]
	v_pk_fma_f32 v[190:191], v[34:35], v[102:103], v[190:191]
	s_waitcnt lgkmcnt(15)
	v_pk_fma_f32 v[192:193], v[36:37], v[100:101], v[192:193]
	v_pk_fma_f32 v[192:193], v[38:39], v[102:103], v[192:193]
	s_waitcnt lgkmcnt(14)
	v_pk_fma_f32 v[194:195], v[40:41], v[100:101], v[194:195]
	v_pk_fma_f32 v[194:195], v[42:43], v[102:103], v[194:195]
	s_waitcnt lgkmcnt(13)
	v_pk_fma_f32 v[196:197], v[44:45], v[100:101], v[196:197]
	v_pk_fma_f32 v[196:197], v[46:47], v[102:103], v[196:197]
	s_waitcnt lgkmcnt(12)
	v_pk_fma_f32 v[198:199], v[48:49], v[100:101], v[198:199]
	v_pk_fma_f32 v[198:199], v[50:51], v[102:103], v[198:199]
	s_waitcnt lgkmcnt(11)
	v_pk_fma_f32 v[200:201], v[52:53], v[100:101], v[200:201]
	v_pk_fma_f32 v[200:201], v[54:55], v[102:103], v[200:201]
	s_waitcnt lgkmcnt(10)
	v_pk_fma_f32 v[202:203], v[56:57], v[100:101], v[202:203]
	v_pk_fma_f32 v[202:203], v[58:59], v[102:103], v[202:203]
	s_waitcnt lgkmcnt(9)
	v_pk_fma_f32 v[204:205], v[60:61], v[100:101], v[204:205]
	v_pk_fma_f32 v[204:205], v[62:63], v[102:103], v[204:205]
	s_waitcnt lgkmcnt(8)
	v_pk_fma_f32 v[206:207], v[64:65], v[100:101], v[206:207]
	v_pk_fma_f32 v[206:207], v[66:67], v[102:103], v[206:207]
	s_waitcnt lgkmcnt(7)
	v_pk_fma_f32 v[208:209], v[68:69], v[100:101], v[208:209]
	v_pk_fma_f32 v[208:209], v[70:71], v[102:103], v[208:209]
	s_waitcnt lgkmcnt(6)
	v_pk_fma_f32 v[210:211], v[72:73], v[100:101], v[210:211]
	v_pk_fma_f32 v[210:211], v[74:75], v[102:103], v[210:211]
	s_waitcnt lgkmcnt(5)
	v_pk_fma_f32 v[212:213], v[76:77], v[100:101], v[212:213]
	v_pk_fma_f32 v[212:213], v[78:79], v[102:103], v[212:213]
	s_waitcnt lgkmcnt(4)
	v_pk_fma_f32 v[214:215], v[80:81], v[100:101], v[214:215]
	v_pk_fma_f32 v[214:215], v[82:83], v[102:103], v[214:215]
	s_waitcnt lgkmcnt(3)
	v_pk_fma_f32 v[216:217], v[84:85], v[100:101], v[216:217]
	v_pk_fma_f32 v[216:217], v[86:87], v[102:103], v[216:217]
	s_waitcnt lgkmcnt(2)
	v_pk_fma_f32 v[218:219], v[88:89], v[100:101], v[218:219]
	v_pk_fma_f32 v[218:219], v[90:91], v[102:103], v[218:219]
	s_waitcnt lgkmcnt(1)
	v_pk_fma_f32 v[220:221], v[92:93], v[100:101], v[220:221]
	v_pk_fma_f32 v[220:221], v[94:95], v[102:103], v[220:221]
	s_waitcnt lgkmcnt(0)
	v_pk_fma_f32 v[222:223], v[96:97], v[100:101], v[222:223]
	v_pk_fma_f32 v[222:223], v[98:99], v[102:103], v[222:223]
	v_add_u32_e32 v31, s6, v3
	s_add_i32 s6, s6, 16
	ds_read_b128 v[32:35], v31
	ds_read_b128 v[36:39], v31 offset:4096
	ds_read_b128 v[40:43], v31 offset:8192
	ds_read_b128 v[44:47], v31 offset:12288
	ds_read_b128 v[48:51], v31 offset:16384
	ds_read_b128 v[52:55], v31 offset:20480
	ds_read_b128 v[56:59], v31 offset:24576
	ds_read_b128 v[60:63], v31 offset:28672
	ds_read_b128 v[64:67], v31 offset:32768
	ds_read_b128 v[68:71], v31 offset:36864
	ds_read_b128 v[72:75], v31 offset:40960
	ds_read_b128 v[76:79], v31 offset:45056
	ds_read_b128 v[80:83], v31 offset:49152
	ds_read_b128 v[84:87], v31 offset:53248
	ds_read_b128 v[88:91], v31 offset:57344
	ds_read_b128 v[92:95], v31 offset:61440
	v_add_u32_e32 v31, 0x10000, v31
	ds_read_b128 v[96:99], v31
	s_waitcnt vmcnt(8)
	s_waitcnt lgkmcnt(15)
	v_pk_fma_f32 v[190:191], v[32:33], v[104:105], v[190:191]
	v_pk_fma_f32 v[190:191], v[34:35], v[106:107], v[190:191]
	s_waitcnt lgkmcnt(15)
	v_pk_fma_f32 v[192:193], v[36:37], v[104:105], v[192:193]
	v_pk_fma_f32 v[192:193], v[38:39], v[106:107], v[192:193]
	s_waitcnt lgkmcnt(14)
	v_pk_fma_f32 v[194:195], v[40:41], v[104:105], v[194:195]
	v_pk_fma_f32 v[194:195], v[42:43], v[106:107], v[194:195]
	s_waitcnt lgkmcnt(13)
	v_pk_fma_f32 v[196:197], v[44:45], v[104:105], v[196:197]
	v_pk_fma_f32 v[196:197], v[46:47], v[106:107], v[196:197]
	s_waitcnt lgkmcnt(12)
	v_pk_fma_f32 v[198:199], v[48:49], v[104:105], v[198:199]
	v_pk_fma_f32 v[198:199], v[50:51], v[106:107], v[198:199]
	s_waitcnt lgkmcnt(11)
	v_pk_fma_f32 v[200:201], v[52:53], v[104:105], v[200:201]
	v_pk_fma_f32 v[200:201], v[54:55], v[106:107], v[200:201]
	s_waitcnt lgkmcnt(10)
	v_pk_fma_f32 v[202:203], v[56:57], v[104:105], v[202:203]
	v_pk_fma_f32 v[202:203], v[58:59], v[106:107], v[202:203]
	s_waitcnt lgkmcnt(9)
	v_pk_fma_f32 v[204:205], v[60:61], v[104:105], v[204:205]
	v_pk_fma_f32 v[204:205], v[62:63], v[106:107], v[204:205]
	s_waitcnt lgkmcnt(8)
	v_pk_fma_f32 v[206:207], v[64:65], v[104:105], v[206:207]
	v_pk_fma_f32 v[206:207], v[66:67], v[106:107], v[206:207]
	s_waitcnt lgkmcnt(7)
	v_pk_fma_f32 v[208:209], v[68:69], v[104:105], v[208:209]
	v_pk_fma_f32 v[208:209], v[70:71], v[106:107], v[208:209]
	s_waitcnt lgkmcnt(6)
	v_pk_fma_f32 v[210:211], v[72:73], v[104:105], v[210:211]
	v_pk_fma_f32 v[210:211], v[74:75], v[106:107], v[210:211]
	s_waitcnt lgkmcnt(5)
	v_pk_fma_f32 v[212:213], v[76:77], v[104:105], v[212:213]
	v_pk_fma_f32 v[212:213], v[78:79], v[106:107], v[212:213]
	s_waitcnt lgkmcnt(4)
	v_pk_fma_f32 v[214:215], v[80:81], v[104:105], v[214:215]
	v_pk_fma_f32 v[214:215], v[82:83], v[106:107], v[214:215]
	s_waitcnt lgkmcnt(3)
	v_pk_fma_f32 v[216:217], v[84:85], v[104:105], v[216:217]
	v_pk_fma_f32 v[216:217], v[86:87], v[106:107], v[216:217]
	s_waitcnt lgkmcnt(2)
	v_pk_fma_f32 v[218:219], v[88:89], v[104:105], v[218:219]
	v_pk_fma_f32 v[218:219], v[90:91], v[106:107], v[218:219]
	s_waitcnt lgkmcnt(1)
	v_pk_fma_f32 v[220:221], v[92:93], v[104:105], v[220:221]
	v_pk_fma_f32 v[220:221], v[94:95], v[106:107], v[220:221]
	s_waitcnt lgkmcnt(0)
	v_pk_fma_f32 v[222:223], v[96:97], v[104:105], v[222:223]
	v_pk_fma_f32 v[222:223], v[98:99], v[106:107], v[222:223]
	v_add_u32_e32 v31, s6, v3
	s_add_i32 s6, s6, 16
	ds_read_b128 v[32:35], v31
	ds_read_b128 v[36:39], v31 offset:4096
	ds_read_b128 v[40:43], v31 offset:8192
	ds_read_b128 v[44:47], v31 offset:12288
	ds_read_b128 v[48:51], v31 offset:16384
	ds_read_b128 v[52:55], v31 offset:20480
	ds_read_b128 v[56:59], v31 offset:24576
	ds_read_b128 v[60:63], v31 offset:28672
	ds_read_b128 v[64:67], v31 offset:32768
	ds_read_b128 v[68:71], v31 offset:36864
	ds_read_b128 v[72:75], v31 offset:40960
	ds_read_b128 v[76:79], v31 offset:45056
	ds_read_b128 v[80:83], v31 offset:49152
	ds_read_b128 v[84:87], v31 offset:53248
	ds_read_b128 v[88:91], v31 offset:57344
	ds_read_b128 v[92:95], v31 offset:61440
	v_add_u32_e32 v31, 0x10000, v31
	ds_read_b128 v[96:99], v31
	s_waitcnt vmcnt(4)
	s_waitcnt lgkmcnt(15)
	v_pk_fma_f32 v[190:191], v[32:33], v[108:109], v[190:191]
	v_pk_fma_f32 v[190:191], v[34:35], v[110:111], v[190:191]
	s_waitcnt lgkmcnt(15)
	v_pk_fma_f32 v[192:193], v[36:37], v[108:109], v[192:193]
	v_pk_fma_f32 v[192:193], v[38:39], v[110:111], v[192:193]
	s_waitcnt lgkmcnt(14)
	v_pk_fma_f32 v[194:195], v[40:41], v[108:109], v[194:195]
	v_pk_fma_f32 v[194:195], v[42:43], v[110:111], v[194:195]
	s_waitcnt lgkmcnt(13)
	v_pk_fma_f32 v[196:197], v[44:45], v[108:109], v[196:197]
	v_pk_fma_f32 v[196:197], v[46:47], v[110:111], v[196:197]
	s_waitcnt lgkmcnt(12)
	v_pk_fma_f32 v[198:199], v[48:49], v[108:109], v[198:199]
	v_pk_fma_f32 v[198:199], v[50:51], v[110:111], v[198:199]
	s_waitcnt lgkmcnt(11)
	v_pk_fma_f32 v[200:201], v[52:53], v[108:109], v[200:201]
	v_pk_fma_f32 v[200:201], v[54:55], v[110:111], v[200:201]
	s_waitcnt lgkmcnt(10)
	v_pk_fma_f32 v[202:203], v[56:57], v[108:109], v[202:203]
	v_pk_fma_f32 v[202:203], v[58:59], v[110:111], v[202:203]
	s_waitcnt lgkmcnt(9)
	v_pk_fma_f32 v[204:205], v[60:61], v[108:109], v[204:205]
	v_pk_fma_f32 v[204:205], v[62:63], v[110:111], v[204:205]
	s_waitcnt lgkmcnt(8)
	v_pk_fma_f32 v[206:207], v[64:65], v[108:109], v[206:207]
	v_pk_fma_f32 v[206:207], v[66:67], v[110:111], v[206:207]
	s_waitcnt lgkmcnt(7)
	v_pk_fma_f32 v[208:209], v[68:69], v[108:109], v[208:209]
	v_pk_fma_f32 v[208:209], v[70:71], v[110:111], v[208:209]
	s_waitcnt lgkmcnt(6)
	v_pk_fma_f32 v[210:211], v[72:73], v[108:109], v[210:211]
	v_pk_fma_f32 v[210:211], v[74:75], v[110:111], v[210:211]
	s_waitcnt lgkmcnt(5)
	v_pk_fma_f32 v[212:213], v[76:77], v[108:109], v[212:213]
	v_pk_fma_f32 v[212:213], v[78:79], v[110:111], v[212:213]
	s_waitcnt lgkmcnt(4)
	v_pk_fma_f32 v[214:215], v[80:81], v[108:109], v[214:215]
	v_pk_fma_f32 v[214:215], v[82:83], v[110:111], v[214:215]
	s_waitcnt lgkmcnt(3)
	v_pk_fma_f32 v[216:217], v[84:85], v[108:109], v[216:217]
	v_pk_fma_f32 v[216:217], v[86:87], v[110:111], v[216:217]
	s_waitcnt lgkmcnt(2)
	v_pk_fma_f32 v[218:219], v[88:89], v[108:109], v[218:219]
	v_pk_fma_f32 v[218:219], v[90:91], v[110:111], v[218:219]
	s_waitcnt lgkmcnt(1)
	v_pk_fma_f32 v[220:221], v[92:93], v[108:109], v[220:221]
	v_pk_fma_f32 v[220:221], v[94:95], v[110:111], v[220:221]
	s_waitcnt lgkmcnt(0)
	v_pk_fma_f32 v[222:223], v[96:97], v[108:109], v[222:223]
	v_pk_fma_f32 v[222:223], v[98:99], v[110:111], v[222:223]
	v_add_u32_e32 v31, s6, v3
	s_add_i32 s6, s6, 16
	ds_read_b128 v[32:35], v31
	ds_read_b128 v[36:39], v31 offset:4096
	ds_read_b128 v[40:43], v31 offset:8192
	ds_read_b128 v[44:47], v31 offset:12288
	ds_read_b128 v[48:51], v31 offset:16384
	ds_read_b128 v[52:55], v31 offset:20480
	ds_read_b128 v[56:59], v31 offset:24576
	ds_read_b128 v[60:63], v31 offset:28672
	ds_read_b128 v[64:67], v31 offset:32768
	ds_read_b128 v[68:71], v31 offset:36864
	ds_read_b128 v[72:75], v31 offset:40960
	ds_read_b128 v[76:79], v31 offset:45056
	ds_read_b128 v[80:83], v31 offset:49152
	ds_read_b128 v[84:87], v31 offset:53248
	ds_read_b128 v[88:91], v31 offset:57344
	ds_read_b128 v[92:95], v31 offset:61440
	v_add_u32_e32 v31, 0x10000, v31
	ds_read_b128 v[96:99], v31
	s_waitcnt vmcnt(0)
	s_waitcnt lgkmcnt(15)
	v_pk_fma_f32 v[190:191], v[32:33], v[112:113], v[190:191]
	v_pk_fma_f32 v[190:191], v[34:35], v[114:115], v[190:191]
	s_waitcnt lgkmcnt(15)
	v_pk_fma_f32 v[192:193], v[36:37], v[112:113], v[192:193]
	v_pk_fma_f32 v[192:193], v[38:39], v[114:115], v[192:193]
	s_waitcnt lgkmcnt(14)
	v_pk_fma_f32 v[194:195], v[40:41], v[112:113], v[194:195]
	v_pk_fma_f32 v[194:195], v[42:43], v[114:115], v[194:195]
	s_waitcnt lgkmcnt(13)
	v_pk_fma_f32 v[196:197], v[44:45], v[112:113], v[196:197]
	v_pk_fma_f32 v[196:197], v[46:47], v[114:115], v[196:197]
	s_waitcnt lgkmcnt(12)
	v_pk_fma_f32 v[198:199], v[48:49], v[112:113], v[198:199]
	v_pk_fma_f32 v[198:199], v[50:51], v[114:115], v[198:199]
	s_waitcnt lgkmcnt(11)
	v_pk_fma_f32 v[200:201], v[52:53], v[112:113], v[200:201]
	v_pk_fma_f32 v[200:201], v[54:55], v[114:115], v[200:201]
	s_waitcnt lgkmcnt(10)
	v_pk_fma_f32 v[202:203], v[56:57], v[112:113], v[202:203]
	v_pk_fma_f32 v[202:203], v[58:59], v[114:115], v[202:203]
	s_waitcnt lgkmcnt(9)
	v_pk_fma_f32 v[204:205], v[60:61], v[112:113], v[204:205]
	v_pk_fma_f32 v[204:205], v[62:63], v[114:115], v[204:205]
	s_waitcnt lgkmcnt(8)
	v_pk_fma_f32 v[206:207], v[64:65], v[112:113], v[206:207]
	v_pk_fma_f32 v[206:207], v[66:67], v[114:115], v[206:207]
	s_waitcnt lgkmcnt(7)
	v_pk_fma_f32 v[208:209], v[68:69], v[112:113], v[208:209]
	v_pk_fma_f32 v[208:209], v[70:71], v[114:115], v[208:209]
	s_waitcnt lgkmcnt(6)
	v_pk_fma_f32 v[210:211], v[72:73], v[112:113], v[210:211]
	v_pk_fma_f32 v[210:211], v[74:75], v[114:115], v[210:211]
	s_waitcnt lgkmcnt(5)
	v_pk_fma_f32 v[212:213], v[76:77], v[112:113], v[212:213]
	v_pk_fma_f32 v[212:213], v[78:79], v[114:115], v[212:213]
	s_waitcnt lgkmcnt(4)
	v_pk_fma_f32 v[214:215], v[80:81], v[112:113], v[214:215]
	v_pk_fma_f32 v[214:215], v[82:83], v[114:115], v[214:215]
	s_waitcnt lgkmcnt(3)
	v_pk_fma_f32 v[216:217], v[84:85], v[112:113], v[216:217]
	v_pk_fma_f32 v[216:217], v[86:87], v[114:115], v[216:217]
	s_waitcnt lgkmcnt(2)
	v_pk_fma_f32 v[218:219], v[88:89], v[112:113], v[218:219]
	v_pk_fma_f32 v[218:219], v[90:91], v[114:115], v[218:219]
	s_waitcnt lgkmcnt(1)
	v_pk_fma_f32 v[220:221], v[92:93], v[112:113], v[220:221]
	v_pk_fma_f32 v[220:221], v[94:95], v[114:115], v[220:221]
	s_waitcnt lgkmcnt(0)
	v_pk_fma_f32 v[222:223], v[96:97], v[112:113], v[222:223]
	v_pk_fma_f32 v[222:223], v[98:99], v[114:115], v[222:223]
	v_add_f32_e32 v12, v190, v191
	v_add_f32_e32 v13, v192, v193
	v_add_f32_e32 v14, v194, v195
	v_add_f32_e32 v15, v196, v197
	v_add_f32_e32 v16, v198, v199
	v_add_f32_e32 v17, v200, v201
	v_add_f32_e32 v18, v202, v203
	v_add_f32_e32 v19, v204, v205
	v_add_f32_e32 v20, v206, v207
	v_add_f32_e32 v21, v208, v209
	v_add_f32_e32 v22, v210, v211
	v_add_f32_e32 v23, v212, v213
	v_add_f32_e32 v24, v214, v215
	v_add_f32_e32 v25, v216, v217
	v_add_f32_e32 v26, v218, v219
	v_add_f32_e32 v27, v220, v221
	v_add_f32_e32 v30, v222, v223
	ds_write2st64_b32 v4, v12, v13 offset1:1
	ds_write2st64_b32 v4, v14, v15 offset0:2 offset1:3
	ds_write2st64_b32 v4, v16, v17 offset0:4 offset1:5
	ds_write2st64_b32 v4, v18, v19 offset0:6 offset1:7
	ds_write2st64_b32 v4, v20, v21 offset0:8 offset1:9
	ds_write2st64_b32 v4, v22, v23 offset0:10 offset1:11
	ds_write2st64_b32 v4, v24, v25 offset0:12 offset1:13
	ds_write2st64_b32 v4, v26, v27 offset0:14 offset1:15
	ds_write_b32 v4, v30 offset:4096
	s_waitcnt lgkmcnt(0)
	s_barrier
	s_and_saveexec_b64 s[6:7], vcc
	s_cbranch_execz .LBB0_407
	s_mul_i32 s0, s16, 0x1800
	s_add_i32 s0, s0, s4
	v_or_b32_e32 v10, s0, v28
	v_readlane_b32 s40, v252, 17
	v_ashrrev_i32_e32 v11, 31, v10
	v_readlane_b32 s50, v252, 27
	v_readlane_b32 s51, v252, 28
	s_mul_i32 s16, s16, 17
	v_lshl_add_u64 v[12:13], s[4:5], 2, v[6:7]
	v_lshl_add_u64 v[10:11], v[10:11], 2, s[50:51]
	s_mov_b64 s[4:5], 0
	v_mov_b32_e32 v14, v2
	v_readlane_b32 s41, v252, 18
	v_readlane_b32 s42, v252, 19
	v_readlane_b32 s43, v252, 20
	v_readlane_b32 s44, v252, 21
	v_readlane_b32 s45, v252, 22
	v_readlane_b32 s46, v252, 23
	v_readlane_b32 s47, v252, 24
	v_readlane_b32 s48, v252, 25
	v_readlane_b32 s49, v252, 26
	v_readlane_b32 s52, v252, 29
	v_readlane_b32 s53, v252, 30
	v_readlane_b32 s54, v252, 31
	v_readlane_b32 s55, v252, 32
